# v9 plus a 4-byte code shift around the E6 K-loop (instruction-fetch alignment)
# baseline (speedup 1.0000x reference)
; #define PG8_STAGE(bufoff, gbase, voff) do { _Pragma("unroll") for (int _i = 0; _i < 2; ++_i) \
;         __builtin_amdgcn_global_load_lds((const unsigned*)((const char*)(gbase) + (voff)[_i]), (LAS unsigned*)(lds + (bufoff) + ldsw + _i * 8192), 16, 0, 0); } while (0)
; #define PG8_STAGE_A(bufoff, ptr, half, rev) do { if (REVA && (rev)) { const char* _p = (ptr) - ((half) ? hstepA : 0); PG8_STAGE(bufoff, _p, voffAr); } else { const char* _p = (ptr) + ((half) ? hstepA : 0); PG8_STAGE(bufoff, _p, voffA); } } while (0)
; #define PG8_LDA(dst, b, h) do { _Pragma("unroll") for (int m = 0; m < 4; ++m) _Pragma("unroll") for (int k = 0; k < 2; ++k) dst[m][k] = *(const LAS bf16x8*)(lds + PG8_SA(b, h) + aoff + m * 2048 + k * 1024); } while (0)
; #define PG8_WAIT_L(n) asm volatile("s_waitcnt lgkmcnt(" #n ")" ::: "memory")
; #define PG8_BAR __builtin_amdgcn_s_barrier()
;     ...
;     for (;;) {
;         const bool has_next = next_unit(ui + 1, nM, nN, MP, nxt, rot);
;         const char* nA = has_next ? nxt.a : cA; const char* nB = has_next ? nxt.b : cB; const char* nAr = has_next ? nxt.ar : cAr; const size_t nHb = has_next ? nxt.hb : cHb;
;         for (int t = 0; t < nt; t += 2) {
;             const bool last = (t == nt - 2);
;             const char* a1 = PG8_APTR(cA, cAr, t + 1); const bool r1 = REVA && ((t + 1) & 4);
;             const char* a2 = last ? nA : PG8_APTR(cA, cAr, t + 2); const bool r2 = REVA && !last && ((t + 2) & 4);
;             const char* a3 = last ? nA + kstep : PG8_APTR(cA, cAr, t + 3); const bool r3 = REVA && !last && ((t + 3) & 4);
;             const char* b2 = last ? nB : cB + (size_t)(t + 2) * kstep; const char* b3 = b2 + kstep; const size_t hb2 = last ? nHb : cHb;
;             PG8_LDB(B0, 0, 0); PG8_SCHED; PG8_LDA(At, 0, 0); PG8_STAGE_A(PG8_SA(1, 1), a1, 1, r1);
;             PG8_WAIT_L(8); PG8_BAR; PG8_WAIT_L(0); PG8_MMA(0, 0, At, B0); PG8_BAR; PG8_SCHED;
;             PG8_LDB(B1, 0, 1); PG8_STAGE(PG8_SB(0, 0), b2, voffB);
;             PG8_BAR; PG8_WAIT_L(0); PG8_MMA(0, 1, At, B1); PG8_BAR;
;     ...
;         for (int a = 0; a < 2; ++a)
; #pragma unroll
;             for (int b = 0; b < 2; ++b)
; #pragma unroll
;                 for (int m = 0; m < 4; ++m)
; #pragma unroll
;                     for (int n = 0; n < 2; ++n) acc[a][b][m][n] = (f32x4){0.f, 0.f, 0.f, 0.f};
;         cur = nxt; cA = nA; cB = nB; cAr = nAr; cHb = nHb; ++ui;
.LBB0_1131:
	s_add_u32 s6, s78, 0x80
	s_addc_u32 s7, s79, 0
	s_add_u32 s8, s0, 0x80080
	s_addc_u32 s9, s1, 0
	v_lshl_add_u64 v[96:97], s[8:9], 0, v[176:177]
	v_lshl_add_u64 v[98:99], s[8:9], 0, v[178:179]
	s_add_u32 s8, s2, 0x100
	v_mov_b32_e32 v0, 0
	s_addc_u32 s9, s3, 0
	s_mov_b32 s26, -2
	s_mov_b64 s[2:3], 0
	v_mov_b32_e32 v1, v0
	v_pk_mov_b32 v[2:3], v[0:1], v[0:1]
	v_pk_mov_b32 v[4:5], v[0:1], v[0:1]
	v_pk_mov_b32 v[6:7], v[0:1], v[0:1]
	v_pk_mov_b32 v[8:9], v[0:1], v[0:1]
	v_pk_mov_b32 v[10:11], v[0:1], v[0:1]
	v_pk_mov_b32 v[12:13], v[0:1], v[0:1]
	v_pk_mov_b32 v[14:15], v[0:1], v[0:1]
	v_pk_mov_b32 v[16:17], v[0:1], v[0:1]
	v_pk_mov_b32 v[18:19], v[0:1], v[0:1]
	v_pk_mov_b32 v[20:21], v[0:1], v[0:1]
	v_pk_mov_b32 v[22:23], v[0:1], v[0:1]
	v_pk_mov_b32 v[24:25], v[0:1], v[0:1]
	v_pk_mov_b32 v[26:27], v[0:1], v[0:1]
	v_pk_mov_b32 v[28:29], v[0:1], v[0:1]
	v_pk_mov_b32 v[30:31], v[0:1], v[0:1]
	v_pk_mov_b32 v[32:33], v[0:1], v[0:1]
	v_pk_mov_b32 v[34:35], v[0:1], v[0:1]
	v_pk_mov_b32 v[36:37], v[0:1], v[0:1]
	v_pk_mov_b32 v[38:39], v[0:1], v[0:1]
	v_pk_mov_b32 v[40:41], v[0:1], v[0:1]
	v_pk_mov_b32 v[42:43], v[0:1], v[0:1]
	v_pk_mov_b32 v[44:45], v[0:1], v[0:1]
	v_pk_mov_b32 v[46:47], v[0:1], v[0:1]
	v_pk_mov_b32 v[48:49], v[0:1], v[0:1]
	v_pk_mov_b32 v[50:51], v[0:1], v[0:1]
	v_pk_mov_b32 v[52:53], v[0:1], v[0:1]
	v_pk_mov_b32 v[54:55], v[0:1], v[0:1]
	v_pk_mov_b32 v[56:57], v[0:1], v[0:1]
	v_pk_mov_b32 v[58:59], v[0:1], v[0:1]
	v_pk_mov_b32 v[60:61], v[0:1], v[0:1]
	v_pk_mov_b32 v[62:63], v[0:1], v[0:1]
	v_pk_mov_b32 v[64:65], v[0:1], v[0:1]
	v_pk_mov_b32 v[66:67], v[0:1], v[0:1]
	v_pk_mov_b32 v[68:69], v[0:1], v[0:1]
	v_pk_mov_b32 v[70:71], v[0:1], v[0:1]
	v_pk_mov_b32 v[72:73], v[0:1], v[0:1]
	v_pk_mov_b32 v[74:75], v[0:1], v[0:1]
	v_pk_mov_b32 v[76:77], v[0:1], v[0:1]
	v_pk_mov_b32 v[78:79], v[0:1], v[0:1]
	v_pk_mov_b32 v[80:81], v[0:1], v[0:1]
	v_pk_mov_b32 v[82:83], v[0:1], v[0:1]
	v_pk_mov_b32 v[84:85], v[0:1], v[0:1]
	v_pk_mov_b32 v[86:87], v[0:1], v[0:1]
	v_pk_mov_b32 v[88:89], v[0:1], v[0:1]
	v_pk_mov_b32 v[90:91], v[0:1], v[0:1]
	v_pk_mov_b32 v[92:93], v[0:1], v[0:1]
	v_pk_mov_b32 v[94:95], v[0:1], v[0:1]
	v_pk_mov_b32 v[100:101], v[0:1], v[0:1]
	v_pk_mov_b32 v[102:103], v[0:1], v[0:1]
	v_pk_mov_b32 v[104:105], v[0:1], v[0:1]
	v_pk_mov_b32 v[106:107], v[0:1], v[0:1]
	v_pk_mov_b32 v[112:113], v[0:1], v[0:1]
	v_pk_mov_b32 v[114:115], v[0:1], v[0:1]
	v_pk_mov_b32 v[116:117], v[0:1], v[0:1]
	v_pk_mov_b32 v[118:119], v[0:1], v[0:1]
	v_pk_mov_b32 v[124:125], v[0:1], v[0:1]
	v_pk_mov_b32 v[126:127], v[0:1], v[0:1]
	v_pk_mov_b32 v[128:129], v[0:1], v[0:1]
	v_pk_mov_b32 v[130:131], v[0:1], v[0:1]
	v_pk_mov_b32 v[136:137], v[0:1], v[0:1]
	v_pk_mov_b32 v[138:139], v[0:1], v[0:1]
	v_pk_mov_b32 v[144:145], v[0:1], v[0:1]
	v_pk_mov_b32 v[146:147], v[0:1], v[0:1]
	s_nop 0
	v_add_u32_e32 v140, 0x10000, v205
	ds_read_b128 v[108:111], v140
	ds_read_b128 v[120:123], v140 offset:1024
	ds_read_b128 v[132:135], v140 offset:2048
	ds_read_b128 v[140:143], v140 offset:3072
.LBB0_1132:
	s_add_u32 s10, s0, s2
	s_addc_u32 s11, s1, s3
	s_add_u32 s16, s10, 0x100
	s_addc_u32 s17, s11, 0
	s_add_u32 s10, s10, 0x180
	s_addc_u32 s11, s11, 0
	s_add_u32 s14, s8, s2
	s_addc_u32 s15, s9, s3
	s_add_i32 s27, 0, 0x10000
	s_cmpk_eq_i32 s2, 0xf00
	s_cselect_b32 s15, s25, s15
	s_cselect_b32 s14, s24, s14
	s_cselect_b32 s21, s79, s17
	s_cselect_b32 s20, s78, s16
	s_cselect_b32 s17, s7, s11
	s_cselect_b32 s16, s6, s10
	v_lshl_add_u64 v[184:185], v[96:97], 0, s[2:3]
	s_add_i32 m0, s70, 0xc000
	ds_read_b128 v[148:151], v209
	ds_read_b128 v[152:155], v209 offset:1024
	ds_read_b128 v[156:159], v209 offset:2048
	ds_read_b128 v[180:183], v209 offset:3072
	ds_read_b128 v[210:213], v209 offset:4096
	ds_read_b128 v[214:217], v209 offset:5120
	ds_read_b128 v[218:221], v209 offset:6144
	ds_read_b128 v[222:225], v209 offset:7168
	global_load_lds_dwordx4 v[184:185], off
	v_lshl_add_u64 v[184:185], v[98:99], 0, s[2:3]
	s_add_i32 m0, s70, 0xe000
	s_nop 0
	global_load_lds_dwordx4 v[184:185], off
	s_waitcnt lgkmcnt(8)
	s_waitcnt vmcnt(10)
	s_barrier
	s_waitcnt lgkmcnt(0)
	v_mfma_f32_16x16x32_bf16 v[144:147], v[108:111], v[148:151], v[144:147]
	v_mfma_f32_16x16x32_bf16 v[136:139], v[132:135], v[148:151], v[136:139]
	v_mfma_f32_16x16x32_bf16 v[116:119], v[108:111], v[156:159], v[116:119]
	v_mfma_f32_16x16x32_bf16 v[112:115], v[132:135], v[156:159], v[112:115]
	v_mfma_f32_16x16x32_bf16 v[92:95], v[108:111], v[210:213], v[92:95]
	v_mfma_f32_16x16x32_bf16 v[88:91], v[132:135], v[210:213], v[88:91]
	v_mfma_f32_16x16x32_bf16 v[76:79], v[108:111], v[218:221], v[76:79]
	v_mfma_f32_16x16x32_bf16 v[72:75], v[132:135], v[218:221], v[72:75]
	v_mfma_f32_16x16x32_bf16 v[144:147], v[120:123], v[152:155], v[144:147]
	v_mfma_f32_16x16x32_bf16 v[136:139], v[140:143], v[152:155], v[136:139]
	v_mfma_f32_16x16x32_bf16 v[116:119], v[120:123], v[180:183], v[116:119]
	v_mfma_f32_16x16x32_bf16 v[112:115], v[140:143], v[180:183], v[112:115]
	v_mfma_f32_16x16x32_bf16 v[92:95], v[120:123], v[214:217], v[92:95]
	v_mfma_f32_16x16x32_bf16 v[88:91], v[140:143], v[214:217], v[88:91]
	v_mfma_f32_16x16x32_bf16 v[76:79], v[120:123], v[222:225], v[76:79]
	v_mfma_f32_16x16x32_bf16 v[72:75], v[140:143], v[222:225], v[72:75]
	s_barrier
	s_add_i32 s10, 0, 0x14000
	v_add_u32_e32 v184, s10, v205
	s_add_i32 s11, s27, s69
	ds_read_b128 v[226:229], v184
	ds_read_b128 v[230:233], v184 offset:1024
	ds_read_b128 v[234:237], v184 offset:2048
	ds_read_b128 v[238:241], v184 offset:3072
	v_lshl_add_u64 v[184:185], s[14:15], 0, v[172:173]
	s_mov_b32 m0, s11
	v_lshl_add_u64 v[190:191], s[14:15], 0, v[168:169]
	global_load_lds_dwordx4 v[184:185], off
	s_add_i32 m0, s11, 0x2000
	s_nop 0
	global_load_lds_dwordx4 v[190:191], off
	s_waitcnt vmcnt(10)
	s_barrier
; #define PG8_STAGE(bufoff, gbase, voff) do { _Pragma("unroll") for (int _i = 0; _i < 2; ++_i) \
;         __builtin_amdgcn_global_load_lds((const unsigned*)((const char*)(gbase) + (voff)[_i]), (LAS unsigned*)(lds + (bufoff) + ldsw + _i * 8192), 16, 0, 0); } while (0)
; #define PG8_STAGE_A(bufoff, ptr, half, rev) do { if (REVA && (rev)) { const char* _p = (ptr) - ((half) ? hstepA : 0); PG8_STAGE(bufoff, _p, voffAr); } else { const char* _p = (ptr) + ((half) ? hstepA : 0); PG8_STAGE(bufoff, _p, voffA); } } while (0)
; #define PG8_LDA(dst, b, h) do { _Pragma("unroll") for (int m = 0; m < 4; ++m) _Pragma("unroll") for (int k = 0; k < 2; ++k) dst[m][k] = *(const LAS bf16x8*)(lds + PG8_SA(b, h) + aoff + m * 2048 + k * 1024); } while (0)
; #define PG8_LDB(dst, b, h) do { _Pragma("unroll") for (int n = 0; n < 2; ++n) _Pragma("unroll") for (int k = 0; k < 2; ++k) dst[n][k] = *(const LAS bf16x8*)(lds + PG8_SB(b, h) + boff + n * 2048 + k * 1024); } while (0)
; #define PG8_MMA(ai, bj, At, Bt) do { __builtin_amdgcn_s_setprio(1); _Pragma("unroll") for (int m = 0; m < 4; ++m) _Pragma("unroll") for (int n = 0; n < 2; ++n) _Pragma("unroll") for (int k = 0; k < 2; ++k) \
;         acc[ai][bj][m][n] = __builtin_amdgcn_mfma_f32_16x16x32_bf16(Bt[n][k], At[m][k], acc[ai][bj][m][n], 0, 0, 0); __builtin_amdgcn_s_setprio(0); } while (0)
; #define PG8_WAIT_V(n) asm volatile("s_waitcnt vmcnt(" #n ")" ::: "memory")
; #define PG8_WAIT_L(n) asm volatile("s_waitcnt lgkmcnt(" #n ")" ::: "memory")
; #define PG8_BAR __builtin_amdgcn_s_barrier()
; #define PG8_SCHED __builtin_amdgcn_sched_barrier(0)
;     ...
;             PG8_BAR; PG8_WAIT_L(0); PG8_MMA(0, 1, At, B1); PG8_BAR;
;             PG8_LDA(At, 0, 1); PG8_STAGE_A(PG8_SA(0, 0), a2, 0, r2);
;             PG8_BAR; PG8_WAIT_L(0); PG8_MMA(1, 0, At, B0); PG8_BAR; PG8_SCHED;
;             PG8_STAGE(PG8_SB(0, 1), b2 + hb2, voffB);
;             PG8_WAIT_V(6); PG8_BAR; PG8_MMA(1, 1, At, B1); PG8_BAR;
;             PG8_LDB(B0, 1, 0); PG8_SCHED; PG8_LDA(At, 1, 0); PG8_STAGE_A(PG8_SA(0, 1), a2, 1, r2);
;             PG8_WAIT_L(8); PG8_BAR; PG8_WAIT_L(0); PG8_MMA(0, 0, At, B0); PG8_BAR; PG8_SCHED;
;             PG8_LDB(B1, 1, 1); PG8_STAGE(PG8_SB(1, 0), b3, voffB);
;             PG8_BAR; PG8_WAIT_L(0); PG8_MMA(0, 1, At, B1); PG8_BAR;
	s_waitcnt lgkmcnt(0)
	v_mfma_f32_16x16x32_bf16 v[128:131], v[226:229], v[148:151], v[128:131]
	v_mfma_f32_16x16x32_bf16 v[124:127], v[234:237], v[148:151], v[124:127]
	v_mfma_f32_16x16x32_bf16 v[104:107], v[226:229], v[156:159], v[104:107]
	v_mfma_f32_16x16x32_bf16 v[100:103], v[234:237], v[156:159], v[100:103]
	v_mfma_f32_16x16x32_bf16 v[84:87], v[226:229], v[210:213], v[84:87]
	v_mfma_f32_16x16x32_bf16 v[80:83], v[234:237], v[210:213], v[80:83]
	v_mfma_f32_16x16x32_bf16 v[68:71], v[226:229], v[218:221], v[68:71]
	v_mfma_f32_16x16x32_bf16 v[64:67], v[234:237], v[218:221], v[64:67]
	v_mfma_f32_16x16x32_bf16 v[128:131], v[230:233], v[152:155], v[128:131]
	v_mfma_f32_16x16x32_bf16 v[124:127], v[238:241], v[152:155], v[124:127]
	v_mfma_f32_16x16x32_bf16 v[104:107], v[230:233], v[180:183], v[104:107]
	v_mfma_f32_16x16x32_bf16 v[100:103], v[238:241], v[180:183], v[100:103]
	v_mfma_f32_16x16x32_bf16 v[84:87], v[230:233], v[214:217], v[84:87]
	v_mfma_f32_16x16x32_bf16 v[80:83], v[238:241], v[214:217], v[80:83]
	v_mfma_f32_16x16x32_bf16 v[68:71], v[230:233], v[222:225], v[68:71]
	v_mfma_f32_16x16x32_bf16 v[64:67], v[238:241], v[222:225], v[64:67]
	s_mov_b32 m0, s70
	v_lshl_add_u64 v[242:243], s[20:21], 0, v[174:175]
	s_barrier
	ds_read_b128 v[148:151], v209 offset:16384
	ds_read_b128 v[152:155], v209 offset:17408
	ds_read_b128 v[156:159], v209 offset:18432
	ds_read_b128 v[180:183], v209 offset:19456
	ds_read_b128 v[210:213], v209 offset:20480
	ds_read_b128 v[214:217], v209 offset:21504
	ds_read_b128 v[218:221], v209 offset:22528
	ds_read_b128 v[222:225], v209 offset:23552
	global_load_lds_dwordx4 v[242:243], off
	v_lshl_add_u64 v[242:243], s[20:21], 0, v[170:171]
	s_mov_b32 m0, s71
	s_nop 0
	global_load_lds_dwordx4 v[242:243], off
	s_waitcnt vmcnt(10)
	s_barrier
	s_waitcnt lgkmcnt(0)
	v_mfma_f32_16x16x32_bf16 v[60:63], v[108:111], v[148:151], v[60:63]
	v_mfma_f32_16x16x32_bf16 v[56:59], v[132:135], v[148:151], v[56:59]
	v_mfma_f32_16x16x32_bf16 v[44:47], v[108:111], v[156:159], v[44:47]
	v_mfma_f32_16x16x32_bf16 v[40:43], v[132:135], v[156:159], v[40:43]
	v_mfma_f32_16x16x32_bf16 v[28:31], v[108:111], v[210:213], v[28:31]
	v_mfma_f32_16x16x32_bf16 v[24:27], v[132:135], v[210:213], v[24:27]
	v_mfma_f32_16x16x32_bf16 v[12:15], v[108:111], v[218:221], v[12:15]
	v_mfma_f32_16x16x32_bf16 v[8:11], v[132:135], v[218:221], v[8:11]
	v_mfma_f32_16x16x32_bf16 v[60:63], v[120:123], v[152:155], v[60:63]
	v_mfma_f32_16x16x32_bf16 v[56:59], v[140:143], v[152:155], v[56:59]
	v_mfma_f32_16x16x32_bf16 v[44:47], v[120:123], v[180:183], v[44:47]
	v_mfma_f32_16x16x32_bf16 v[40:43], v[140:143], v[180:183], v[40:43]
	v_mfma_f32_16x16x32_bf16 v[28:31], v[120:123], v[214:217], v[28:31]
	v_mfma_f32_16x16x32_bf16 v[24:27], v[140:143], v[214:217], v[24:27]
	v_mfma_f32_16x16x32_bf16 v[12:15], v[120:123], v[222:225], v[12:15]
	v_mfma_f32_16x16x32_bf16 v[8:11], v[140:143], v[222:225], v[8:11]
	s_barrier
	s_add_u32 s36, s14, 0x80000
	s_addc_u32 s37, s15, 0
	s_add_i32 s10, s10, s69
	v_lshl_add_u64 v[108:109], s[36:37], 0, v[172:173]
	s_mov_b32 m0, s10
	s_nop 0
	global_load_lds_dwordx4 v[108:109], off
	v_lshl_add_u64 v[108:109], s[36:37], 0, v[168:169]
	s_add_i32 m0, s10, 0x2000
	s_nop 0
	global_load_lds_dwordx4 v[108:109], off
	v_add_u32_e32 v140, 0x18000, v205
	ds_read_b128 v[108:111], v140
	ds_read_b128 v[120:123], v140 offset:1024
	ds_read_b128 v[132:135], v140 offset:2048
	ds_read_b128 v[140:143], v140 offset:3072
	s_waitcnt vmcnt(10)
	s_barrier
	v_mfma_f32_16x16x32_bf16 v[52:55], v[226:229], v[148:151], v[52:55]
	v_mfma_f32_16x16x32_bf16 v[48:51], v[234:237], v[148:151], v[48:51]
	v_mfma_f32_16x16x32_bf16 v[36:39], v[226:229], v[156:159], v[36:39]
	v_mfma_f32_16x16x32_bf16 v[32:35], v[234:237], v[156:159], v[32:35]
	v_mfma_f32_16x16x32_bf16 v[20:23], v[226:229], v[210:213], v[20:23]
	v_mfma_f32_16x16x32_bf16 v[16:19], v[234:237], v[210:213], v[16:19]
	v_mfma_f32_16x16x32_bf16 v[4:7], v[226:229], v[218:221], v[4:7]
	v_mfma_f32_16x16x32_bf16 v[0:3], v[234:237], v[218:221], v[0:3]
	v_mfma_f32_16x16x32_bf16 v[52:55], v[230:233], v[152:155], v[52:55]
	v_mfma_f32_16x16x32_bf16 v[48:51], v[238:241], v[152:155], v[48:51]
	v_mfma_f32_16x16x32_bf16 v[36:39], v[230:233], v[180:183], v[36:39]
	v_mfma_f32_16x16x32_bf16 v[32:35], v[238:241], v[180:183], v[32:35]
	v_mfma_f32_16x16x32_bf16 v[20:23], v[230:233], v[214:217], v[20:23]
	v_mfma_f32_16x16x32_bf16 v[16:19], v[238:241], v[214:217], v[16:19]
	v_mfma_f32_16x16x32_bf16 v[4:7], v[230:233], v[222:225], v[4:7]
	v_mfma_f32_16x16x32_bf16 v[0:3], v[238:241], v[222:225], v[0:3]
	s_add_i32 s10, 0, 0x18000
	s_barrier
	s_add_u32 s20, s20, 0x80000
	s_addc_u32 s21, s21, 0
	s_mov_b32 m0, s89
	v_lshl_add_u64 v[226:227], s[20:21], 0, v[174:175]
	ds_read_b128 v[148:151], v209 offset:32768
	ds_read_b128 v[152:155], v209 offset:33792
	ds_read_b128 v[156:159], v209 offset:34816
	ds_read_b128 v[180:183], v209 offset:35840
	ds_read_b128 v[210:213], v209 offset:36864
	ds_read_b128 v[214:217], v209 offset:37888
	ds_read_b128 v[218:221], v209 offset:38912
	ds_read_b128 v[222:225], v209 offset:39936
	global_load_lds_dwordx4 v[226:227], off
	v_lshl_add_u64 v[226:227], s[20:21], 0, v[170:171]
	s_mov_b32 m0, s90
	s_nop 0
	global_load_lds_dwordx4 v[226:227], off
	s_waitcnt lgkmcnt(8)
	s_waitcnt vmcnt(10)
	s_barrier
; #define PG8_STAGE(bufoff, gbase, voff) do { _Pragma("unroll") for (int _i = 0; _i < 2; ++_i) \
;         __builtin_amdgcn_global_load_lds((const unsigned*)((const char*)(gbase) + (voff)[_i]), (LAS unsigned*)(lds + (bufoff) + ldsw + _i * 8192), 16, 0, 0); } while (0)
; #define PG8_STAGE_A(bufoff, ptr, half, rev) do { if (REVA && (rev)) { const char* _p = (ptr) - ((half) ? hstepA : 0); PG8_STAGE(bufoff, _p, voffAr); } else { const char* _p = (ptr) + ((half) ? hstepA : 0); PG8_STAGE(bufoff, _p, voffA); } } while (0)
; #define PG8_LDA(dst, b, h) do { _Pragma("unroll") for (int m = 0; m < 4; ++m) _Pragma("unroll") for (int k = 0; k < 2; ++k) dst[m][k] = *(const LAS bf16x8*)(lds + PG8_SA(b, h) + aoff + m * 2048 + k * 1024); } while (0)
; #define PG8_LDB(dst, b, h) do { _Pragma("unroll") for (int n = 0; n < 2; ++n) _Pragma("unroll") for (int k = 0; k < 2; ++k) dst[n][k] = *(const LAS bf16x8*)(lds + PG8_SB(b, h) + boff + n * 2048 + k * 1024); } while (0)
; #define PG8_MMA(ai, bj, At, Bt) do { __builtin_amdgcn_s_setprio(1); _Pragma("unroll") for (int m = 0; m < 4; ++m) _Pragma("unroll") for (int n = 0; n < 2; ++n) _Pragma("unroll") for (int k = 0; k < 2; ++k) \
;         acc[ai][bj][m][n] = __builtin_amdgcn_mfma_f32_16x16x32_bf16(Bt[n][k], At[m][k], acc[ai][bj][m][n], 0, 0, 0); __builtin_amdgcn_s_setprio(0); } while (0)
; #define PG8_WAIT_L(n) asm volatile("s_waitcnt lgkmcnt(" #n ")" ::: "memory")
; #define PG8_BAR __builtin_amdgcn_s_barrier()
; #define PG8_SCHED __builtin_amdgcn_sched_barrier(0)
;     ...
;             PG8_LDB(B0, 1, 0); PG8_SCHED; PG8_LDA(At, 1, 0); PG8_STAGE_A(PG8_SA(0, 1), a2, 1, r2);
;             PG8_WAIT_L(8); PG8_BAR; PG8_WAIT_L(0); PG8_MMA(0, 0, At, B0); PG8_BAR; PG8_SCHED;
;             PG8_LDB(B1, 1, 1); PG8_STAGE(PG8_SB(1, 0), b3, voffB);
;             PG8_BAR; PG8_WAIT_L(0); PG8_MMA(0, 1, At, B1); PG8_BAR;
;             PG8_LDA(At, 1, 1); PG8_STAGE_A(PG8_SA(1, 0), a3, 0, r3);
;             PG8_BAR; PG8_WAIT_L(0); PG8_MMA(1, 0, At, B0); PG8_BAR; PG8_SCHED;
	s_waitcnt lgkmcnt(0)
	v_mfma_f32_16x16x32_bf16 v[144:147], v[108:111], v[148:151], v[144:147]
	v_mfma_f32_16x16x32_bf16 v[136:139], v[132:135], v[148:151], v[136:139]
	v_mfma_f32_16x16x32_bf16 v[116:119], v[108:111], v[156:159], v[116:119]
	v_mfma_f32_16x16x32_bf16 v[112:115], v[132:135], v[156:159], v[112:115]
	v_mfma_f32_16x16x32_bf16 v[92:95], v[108:111], v[210:213], v[92:95]
	v_mfma_f32_16x16x32_bf16 v[88:91], v[132:135], v[210:213], v[88:91]
	v_mfma_f32_16x16x32_bf16 v[76:79], v[108:111], v[218:221], v[76:79]
	v_mfma_f32_16x16x32_bf16 v[72:75], v[132:135], v[218:221], v[72:75]
	v_mfma_f32_16x16x32_bf16 v[144:147], v[120:123], v[152:155], v[144:147]
	v_mfma_f32_16x16x32_bf16 v[136:139], v[140:143], v[152:155], v[136:139]
	v_mfma_f32_16x16x32_bf16 v[116:119], v[120:123], v[180:183], v[116:119]
	v_mfma_f32_16x16x32_bf16 v[112:115], v[140:143], v[180:183], v[112:115]
	v_mfma_f32_16x16x32_bf16 v[92:95], v[120:123], v[214:217], v[92:95]
	v_mfma_f32_16x16x32_bf16 v[88:91], v[140:143], v[214:217], v[88:91]
	v_mfma_f32_16x16x32_bf16 v[76:79], v[120:123], v[222:225], v[76:79]
	v_mfma_f32_16x16x32_bf16 v[72:75], v[140:143], v[222:225], v[72:75]
	s_barrier
	s_add_i32 s11, 0, 0x1c000
	s_add_i32 s10, s10, s69
	v_add_u32_e32 v238, s11, v205
	v_lshl_add_u64 v[184:185], v[184:185], 0, s[28:29]
	s_mov_b32 m0, s10
	ds_read_b128 v[226:229], v238
	ds_read_b128 v[230:233], v238 offset:1024
	ds_read_b128 v[234:237], v238 offset:2048
	ds_read_b128 v[238:241], v238 offset:3072
	global_load_lds_dwordx4 v[184:185], off
	v_lshl_add_u64 v[184:185], v[190:191], 0, s[28:29]
	s_add_i32 m0, s10, 0x2000
	s_nop 0
	global_load_lds_dwordx4 v[184:185], off
	s_waitcnt vmcnt(10)
	s_barrier
	s_waitcnt lgkmcnt(0)
	v_mfma_f32_16x16x32_bf16 v[128:131], v[226:229], v[148:151], v[128:131]
	v_mfma_f32_16x16x32_bf16 v[124:127], v[234:237], v[148:151], v[124:127]
	v_mfma_f32_16x16x32_bf16 v[104:107], v[226:229], v[156:159], v[104:107]
	v_mfma_f32_16x16x32_bf16 v[100:103], v[234:237], v[156:159], v[100:103]
	v_mfma_f32_16x16x32_bf16 v[84:87], v[226:229], v[210:213], v[84:87]
	v_mfma_f32_16x16x32_bf16 v[80:83], v[234:237], v[210:213], v[80:83]
	v_mfma_f32_16x16x32_bf16 v[68:71], v[226:229], v[218:221], v[68:71]
	v_mfma_f32_16x16x32_bf16 v[64:67], v[234:237], v[218:221], v[64:67]
	v_mfma_f32_16x16x32_bf16 v[128:131], v[230:233], v[152:155], v[128:131]
	v_mfma_f32_16x16x32_bf16 v[124:127], v[238:241], v[152:155], v[124:127]
	v_mfma_f32_16x16x32_bf16 v[104:107], v[230:233], v[180:183], v[104:107]
	v_mfma_f32_16x16x32_bf16 v[100:103], v[238:241], v[180:183], v[100:103]
	v_mfma_f32_16x16x32_bf16 v[84:87], v[230:233], v[214:217], v[84:87]
	v_mfma_f32_16x16x32_bf16 v[80:83], v[238:241], v[214:217], v[80:83]
	v_mfma_f32_16x16x32_bf16 v[68:71], v[230:233], v[222:225], v[68:71]
	v_mfma_f32_16x16x32_bf16 v[64:67], v[238:241], v[222:225], v[64:67]
	s_mov_b32 m0, s97
	v_lshl_add_u64 v[184:185], s[16:17], 0, v[174:175]
	s_barrier
	ds_read_b128 v[148:151], v209 offset:49152
	ds_read_b128 v[152:155], v209 offset:50176
	ds_read_b128 v[156:159], v209 offset:51200
	ds_read_b128 v[180:183], v209 offset:52224
	ds_read_b128 v[210:213], v209 offset:53248
	ds_read_b128 v[214:217], v209 offset:54272
	ds_read_b128 v[218:221], v209 offset:55296
	ds_read_b128 v[222:225], v209 offset:56320
	global_load_lds_dwordx4 v[184:185], off
	v_lshl_add_u64 v[184:185], s[16:17], 0, v[170:171]
	s_mov_b32 m0, s52
	s_nop 0
	global_load_lds_dwordx4 v[184:185], off
	s_waitcnt vmcnt(10)
	s_barrier
; #define PG8_STAGE(bufoff, gbase, voff) do { _Pragma("unroll") for (int _i = 0; _i < 2; ++_i) \
;         __builtin_amdgcn_global_load_lds((const unsigned*)((const char*)(gbase) + (voff)[_i]), (LAS unsigned*)(lds + (bufoff) + ldsw + _i * 8192), 16, 0, 0); } while (0)
; #define PG8_MMA(ai, bj, At, Bt) do { __builtin_amdgcn_s_setprio(1); _Pragma("unroll") for (int m = 0; m < 4; ++m) _Pragma("unroll") for (int n = 0; n < 2; ++n) _Pragma("unroll") for (int k = 0; k < 2; ++k) \
;         acc[ai][bj][m][n] = __builtin_amdgcn_mfma_f32_16x16x32_bf16(Bt[n][k], At[m][k], acc[ai][bj][m][n], 0, 0, 0); __builtin_amdgcn_s_setprio(0); } while (0)
; #define PG8_WAIT_V(n) asm volatile("s_waitcnt vmcnt(" #n ")" ::: "memory")
; #define PG8_WAIT_L(n) asm volatile("s_waitcnt lgkmcnt(" #n ")" ::: "memory")
; #define PG8_BAR __builtin_amdgcn_s_barrier()
; #define PG8_SCHED __builtin_amdgcn_sched_barrier(0)
;     ...
;             PG8_BAR; PG8_WAIT_L(0); PG8_MMA(1, 0, At, B0); PG8_BAR; PG8_SCHED;
;             PG8_STAGE(PG8_SB(1, 1), b3 + hb2, voffB);
;             PG8_WAIT_V(6); PG8_BAR; PG8_MMA(1, 1, At, B1); PG8_BAR;
;         }
;         E(acc, cur, wr, wc, fr, fq, lane);
;     __device__ __forceinline__ void gates(const f32x4 (&acc)[2][2][4][2], const Unit& u, int wr, int wc, int fr, int fq) const {
;         const bool ret = u.pn < 8;
;         const bf16_t* mulp = ret ? (OFp + u.pn * BM) : (Y + (u.pn - 8) * BM);
; #pragma unroll
;         for (int ai = 0; ai < 2; ++ai) {
;             u32x4 yv[4][2]; float rs[4];
; #pragma unroll
;             for (int m = 0; m < 4; ++m) {
;                 const size_t row = (size_t)(u.pm * BM + ai * HALF + wr * 64 + m * 16 + fr);
; #pragma unroll
;                 for (int bj = 0; bj < 2; ++bj) yv[m][bj] = *(const u32x4*)(mulp + row * 2048 + bj * HALF + wc * 32 + 8 * fq);
;                 rs[m] = 1.0f;
;                 if (ret) { const f32x4 sq = *(const f32x4*)(SSp + row * 32 + u.pn * 4); rs[m] = rsqrtf((sq[0] + sq[1] + sq[2] + sq[3]) * (1.0f / 256.0f) + 1e-6f); }
	s_waitcnt lgkmcnt(0)
	v_mfma_f32_16x16x32_bf16 v[60:63], v[108:111], v[148:151], v[60:63]
	v_mfma_f32_16x16x32_bf16 v[56:59], v[132:135], v[148:151], v[56:59]
	v_mfma_f32_16x16x32_bf16 v[44:47], v[108:111], v[156:159], v[44:47]
	v_mfma_f32_16x16x32_bf16 v[40:43], v[132:135], v[156:159], v[40:43]
	v_mfma_f32_16x16x32_bf16 v[28:31], v[108:111], v[210:213], v[28:31]
	v_mfma_f32_16x16x32_bf16 v[24:27], v[132:135], v[210:213], v[24:27]
	v_mfma_f32_16x16x32_bf16 v[12:15], v[108:111], v[218:221], v[12:15]
	v_mfma_f32_16x16x32_bf16 v[8:11], v[132:135], v[218:221], v[8:11]
	v_mfma_f32_16x16x32_bf16 v[60:63], v[120:123], v[152:155], v[60:63]
	v_mfma_f32_16x16x32_bf16 v[56:59], v[140:143], v[152:155], v[56:59]
	v_mfma_f32_16x16x32_bf16 v[44:47], v[120:123], v[180:183], v[44:47]
	v_mfma_f32_16x16x32_bf16 v[40:43], v[140:143], v[180:183], v[40:43]
	v_mfma_f32_16x16x32_bf16 v[28:31], v[120:123], v[214:217], v[28:31]
	v_mfma_f32_16x16x32_bf16 v[24:27], v[140:143], v[214:217], v[24:27]
	v_mfma_f32_16x16x32_bf16 v[12:15], v[120:123], v[222:225], v[12:15]
	v_mfma_f32_16x16x32_bf16 v[8:11], v[140:143], v[222:225], v[8:11]
	s_barrier
	s_add_u32 s14, s14, 0x80080
	s_addc_u32 s15, s15, 0
	s_add_i32 s10, s11, s69
	v_lshl_add_u64 v[108:109], s[14:15], 0, v[172:173]
	s_mov_b32 m0, s10
	s_nop 0
	global_load_lds_dwordx4 v[108:109], off
	v_lshl_add_u64 v[108:109], s[14:15], 0, v[168:169]
	s_add_i32 m0, s10, 0x2000
	s_nop 0
	global_load_lds_dwordx4 v[108:109], off
	v_add_u32_e32 v140, 0x10000, v205
	ds_read_b128 v[108:111], v140
	ds_read_b128 v[120:123], v140 offset:1024
	ds_read_b128 v[132:135], v140 offset:2048
	ds_read_b128 v[140:143], v140 offset:3072
	s_waitcnt vmcnt(10)
	s_barrier
	v_mfma_f32_16x16x32_bf16 v[52:55], v[226:229], v[148:151], v[52:55]
	v_mfma_f32_16x16x32_bf16 v[48:51], v[234:237], v[148:151], v[48:51]
	v_mfma_f32_16x16x32_bf16 v[36:39], v[226:229], v[156:159], v[36:39]
	v_mfma_f32_16x16x32_bf16 v[32:35], v[234:237], v[156:159], v[32:35]
	v_mfma_f32_16x16x32_bf16 v[20:23], v[226:229], v[210:213], v[20:23]
	v_mfma_f32_16x16x32_bf16 v[16:19], v[234:237], v[210:213], v[16:19]
	v_mfma_f32_16x16x32_bf16 v[4:7], v[226:229], v[218:221], v[4:7]
	v_mfma_f32_16x16x32_bf16 v[0:3], v[234:237], v[218:221], v[0:3]
	v_mfma_f32_16x16x32_bf16 v[52:55], v[230:233], v[152:155], v[52:55]
	v_mfma_f32_16x16x32_bf16 v[48:51], v[238:241], v[152:155], v[48:51]
	v_mfma_f32_16x16x32_bf16 v[36:39], v[230:233], v[180:183], v[36:39]
	v_mfma_f32_16x16x32_bf16 v[32:35], v[238:241], v[180:183], v[32:35]
	v_mfma_f32_16x16x32_bf16 v[20:23], v[230:233], v[214:217], v[20:23]
	v_mfma_f32_16x16x32_bf16 v[16:19], v[238:241], v[214:217], v[16:19]
	v_mfma_f32_16x16x32_bf16 v[4:7], v[230:233], v[222:225], v[4:7]
	v_mfma_f32_16x16x32_bf16 v[0:3], v[238:241], v[222:225], v[0:3]
	s_add_i32 s26, s26, 2
	s_add_u32 s2, s2, 0x100
	s_addc_u32 s3, s3, 0
	s_cmp_gt_u32 s26, 29
	s_barrier
	s_cbranch_scc0 .LBB0_1132
	s_waitcnt lgkmcnt(0)
	s_nop 0
	s_lshl_b32 s0, s4, 8
	s_ashr_i32 s1, s0, 31
	s_lshl_b64 s[26:27], s[0:1], 1
	s_add_u32 s6, s93, s26
	s_addc_u32 s7, s94, s27
	s_addk_i32 s0, 0xf800
	s_mov_b32 s1, s23
	s_lshl_b64 s[0:1], s[0:1], 1
	s_add_u32 s8, s91, s0
	s_addc_u32 s9, s92, s1
	s_cmp_lt_i32 s4, 8
	s_cselect_b64 s[0:1], -1, 0
	s_and_b64 s[2:3], s[0:1], exec
	s_cselect_b32 s3, s6, s8
	s_cselect_b32 s2, s7, s9
	s_add_u32 s6, s3, s22
	s_addc_u32 s7, s2, 0
	s_lshl_b32 s2, s5, 8
	v_add_u32_e32 v180, s2, v204
	v_ashrrev_i32_e32 v181, 31, v180
	v_lshl_add_u64 v[182:183], s[6:7], 0, v[160:161]
	v_lshlrev_b64 v[96:97], 12, v[180:181]
	v_lshl_add_u64 v[96:97], v[182:183], 0, v[96:97]
	global_load_dwordx4 v[156:159], v[96:97], off
	global_load_dwordx4 v[152:155], v[96:97], off offset:256
	s_lshl_b32 s6, s4, 2
	s_ashr_i32 s7, s6, 31
	s_lshl_b64 s[6:7], s[6:7], 2
	s_add_u32 s36, s95, s6
	s_addc_u32 s37, s96, s7
	s_cmp_gt_i32 s4, 7
	v_mov_b32_e32 v212, 1.0
	v_mov_b32_e32 v213, 1.0
	s_cbranch_scc1 .LBB0_1135
	v_lshlrev_b64 v[96:97], 7, v[180:181]
	v_lshl_add_u64 v[96:97], s[36:37], 0, v[96:97]
	global_load_dwordx4 v[96:99], v[96:97], off
	s_waitcnt vmcnt(0)
	v_add_f32_e32 v96, v96, v97
	v_add_f32_e32 v96, v98, v96
	v_add_f32_e32 v96, v99, v96
	v_fmamk_f32 v96, v96, 0x3b800000, v194
	v_mul_f32_e32 v97, 0x4b800000, v96
	v_cmp_gt_f32_e32 vcc, s55, v96
	s_nop 1
	v_cndmask_b32_e32 v96, v96, v97, vcc
	v_rsq_f32_e32 v96, v96
	s_nop 0
	v_mul_f32_e32 v97, 0x45800000, v96
	v_cndmask_b32_e32 v213, v96, v97, vcc
